# static s_setprio 1 removed from all 15 GEMM phases (both wave halves at equal priority); on top of norm-loop consolidation
# speedup vs baseline: 1.0016x; 1.0001x over previous
; #define PG8_STAGE(bufoff, gbase, voff) do { if constexpr (!NOSTAGE) _Pragma("unroll") for (int _i = 0; _i < 2; ++_i) \
;         __builtin_amdgcn_global_load_lds((const unsigned*)((const char*)(gbase) + (size_t)_i * pstep##voff + v##voff), (PG8_LAS unsigned*)(lds + (bufoff) + ldsw + _i * 8192), 16, 0, 0); } while (0)
; #define PG8_WAIT_V(n) asm volatile("s_waitcnt vmcnt(" #n ")" ::: "memory")
; #define PG8_BAR __builtin_amdgcn_s_barrier()
; template <class Epi, class Sched, bool ALIGN_EPI = true, bool SP2 = true, bool FULLLINE = false, bool NOSTAGE = false, bool FP8 = false>
; __device__ __forceinline__ void gemm_phase(PG8_LAS unsigned char* lds, const Gemm g, const Sched& S, const Epi& E) {
;     ...
;     if (wr == 1) PG8_BAR;
;     PG8_WAIT_V(0); PG8_BAR;
;     PG8_BAR;
;     } else {
;     PG8_STAGE(PG8_SB(0, 0), cB, offB); PG8_STAGE(PG8_SA(0, 0), cA, offA); PG8_STAGE(PG8_SB(0, 1), cB + hstepB, offB); PG8_STAGE(PG8_SA(0, 1), cA + hstepA, offA);
;     if (wr == 1) PG8_BAR;
;     PG8_WAIT_V(4); PG8_BAR;
;     PG8_STAGE(PG8_SB(1, 0), cB + kstep, offB); PG8_STAGE(PG8_SA(1, 0), cA + kstep, offA); PG8_STAGE(PG8_SB(1, 1), cB + hstepB + kstep, offB);
;     PG8_WAIT_V(6); PG8_BAR;
;     }
;     if (wr == 1) __builtin_amdgcn_s_setprio(1);
.LBB0_254:
	s_waitcnt vmcnt(0)
	v_cndmask_b32_e64 v4, 0, 1, s[8:9]
	v_cmp_ne_u32_e64 s[6:7], 1, v4
	s_andn2_b64 vcc, exec, s[8:9]
	s_barrier
	s_barrier
	s_cbranch_vccnz .LBB0_256
	s_nop 0

; #define PG8_STAGE(bufoff, gbase, voff) do { if constexpr (!NOSTAGE) _Pragma("unroll") for (int _i = 0; _i < 2; ++_i) \
;         __builtin_amdgcn_global_load_lds((const unsigned*)((const char*)(gbase) + (size_t)_i * pstep##voff + v##voff), (PG8_LAS unsigned*)(lds + (bufoff) + ldsw + _i * 8192), 16, 0, 0); } while (0)
; #define PG8_WAIT_V(n) asm volatile("s_waitcnt vmcnt(" #n ")" ::: "memory")
; #define PG8_BAR __builtin_amdgcn_s_barrier()
; template <class Epi, class Sched, bool ALIGN_EPI = true, bool SP2 = true, bool FULLLINE = false, bool NOSTAGE = false, bool FP8 = false>
; __device__ __forceinline__ void gemm_phase(PG8_LAS unsigned char* lds, const Gemm g, const Sched& S, const Epi& E) {
;     ...
;     if (wr == 1) PG8_BAR;
;     PG8_WAIT_V(0); PG8_BAR;
;     PG8_BAR;
;     } else {
;     PG8_STAGE(PG8_SB(0, 0), cB, offB); PG8_STAGE(PG8_SA(0, 0), cA, offA); PG8_STAGE(PG8_SB(0, 1), cB + hstepB, offB); PG8_STAGE(PG8_SA(0, 1), cA + hstepA, offA);
;     if (wr == 1) PG8_BAR;
;     PG8_WAIT_V(4); PG8_BAR;
;     PG8_STAGE(PG8_SB(1, 0), cB + kstep, offB); PG8_STAGE(PG8_SA(1, 0), cA + kstep, offA); PG8_STAGE(PG8_SB(1, 1), cB + hstepB + kstep, offB);
;     PG8_WAIT_V(6); PG8_BAR;
;     }
;     if (wr == 1) __builtin_amdgcn_s_setprio(1);
.LBB0_582:
	s_waitcnt vmcnt(0)
	v_cndmask_b32_e64 v4, 0, 1, s[10:11]
	v_cmp_ne_u32_e64 s[6:7], 1, v4
	s_andn2_b64 vcc, exec, s[10:11]
	s_barrier
	s_barrier
	s_cbranch_vccnz .LBB0_584
	s_nop 0

; #define PG8_STAGE(bufoff, gbase, voff) do { if constexpr (!NOSTAGE) _Pragma("unroll") for (int _i = 0; _i < 2; ++_i) \
;         __builtin_amdgcn_global_load_lds((const unsigned*)((const char*)(gbase) + (size_t)_i * pstep##voff + v##voff), (PG8_LAS unsigned*)(lds + (bufoff) + ldsw + _i * 8192), 16, 0, 0); } while (0)
; #define PG8_WAIT_V(n) asm volatile("s_waitcnt vmcnt(" #n ")" ::: "memory")
; #define PG8_BAR __builtin_amdgcn_s_barrier()
; template <class Epi, class Sched, bool ALIGN_EPI = true, bool SP2 = true, bool FULLLINE = false, bool NOSTAGE = false, bool FP8 = false>
; __device__ __forceinline__ void gemm_phase(PG8_LAS unsigned char* lds, const Gemm g, const Sched& S, const Epi& E) {
;     ...
;     if (wr == 1) PG8_BAR;
;     PG8_WAIT_V(0); PG8_BAR;
;     PG8_BAR;
;     } else {
;     PG8_STAGE(PG8_SB(0, 0), cB, offB); PG8_STAGE(PG8_SA(0, 0), cA, offA); PG8_STAGE(PG8_SB(0, 1), cB + hstepB, offB); PG8_STAGE(PG8_SA(0, 1), cA + hstepA, offA);
;     if (wr == 1) PG8_BAR;
;     PG8_WAIT_V(4); PG8_BAR;
;     PG8_STAGE(PG8_SB(1, 0), cB + kstep, offB); PG8_STAGE(PG8_SA(1, 0), cA + kstep, offA); PG8_STAGE(PG8_SB(1, 1), cB + hstepB + kstep, offB);
;     PG8_WAIT_V(6); PG8_BAR;
;     }
;     if (wr == 1) __builtin_amdgcn_s_setprio(1);
.LBB0_854:
	s_waitcnt vmcnt(0)
	v_cndmask_b32_e64 v4, 0, 1, s[8:9]
	s_lshr_b32 s13, s6, 3
	v_cmp_ne_u32_e64 s[6:7], 1, v4
	s_andn2_b64 vcc, exec, s[8:9]
	s_barrier
	s_barrier
	s_cbranch_vccnz .LBB0_856
	s_nop 0
